# attention: P.V split by key half, second half of the softmax (exp/sum/pack) runs in the shadow of the first 8 P.V MFMAs
# speedup vs baseline: 1.0047x; 1.0047x over previous
; #define LAS __attribute__((address_space(3)))
; __device__ __forceinline__ unsigned cvtpk_s(float lo, float hi) { f32x2_t v = {lo, hi}; bf16x2_t b = __builtin_convertvector(v, bf16x2_t); return __builtin_bit_cast(unsigned, b); }
; template <int HF> ...
;     ...
;         float ls = 0.f;
; #pragma unroll
;         for (int r = 0; r < 16; ++r) { p[r] = __builtin_amdgcn_exp2f(p[r]); ls += p[r]; }
;         lsum[sub] += ls;
;         pw[sub][0] = (u32x4){cvtpk_s(p[0], p[1]), cvtpk_s(p[2], p[3]), cvtpk_s(p[4], p[5]), cvtpk_s(p[6], p[7])};
;         pw[sub][1] = (u32x4){cvtpk_s(p[8], p[9]), cvtpk_s(p[10], p[11]), cvtpk_s(p[12], p[13]), cvtpk_s(p[14], p[15])};
;         __builtin_amdgcn_sched_barrier(0);
;         if (sub == 0 && stage) {
;             if (HF == 0) { *(LAS u32x4*)sdst = st0; *(LAS u32x4*)(sdst + 32 * KROW) = st1; }
;             else { *(LAS u32x2*)sdst = (u32x2){st0.x, st0.y}; *(LAS u32x2*)(sdst + 8) = (u32x2){st0.z, st0.w}; *(LAS u32x2*)(sdst + 64 * VROW) = (u32x2){st1.x, st1.y}; *(LAS u32x2*)(sdst + 64 * VROW + 8) = (u32x2){st1.z, st1.w}; }
;             __builtin_amdgcn_sched_barrier(0);
;         }
;     }
;     ...
;     bf16x8 vcur = AT_VFRAG(0);
;     __builtin_amdgcn_s_setprio(1);
; #pragma unroll
;     for (int idx = 0; idx < 8; ++idx) {
;         bf16x8 vnext = vcur;
;         if (idx + 1 < 8) vnext = AT_VFRAG(idx + 1);
;         const int kk = idx >> 2, d = idx & 3;
;         o[0][d] = __builtin_amdgcn_mfma_f32_32x32x16_bf16(vcur, __builtin_bit_cast(bf16x8, pw[0][kk]), o[0][d], 0, 0, 0);
;         o[1][d] = __builtin_amdgcn_mfma_f32_32x32x16_bf16(vcur, __builtin_bit_cast(bf16x8, pw[1][kk]), o[1][d], 0, 0, 0);
;         __builtin_amdgcn_sched_barrier(0);
;         vcur = vnext;
;     }
;     __builtin_amdgcn_s_setprio(0);
.LBB0_258:
	s_add_i32 s96, s91, 0x8800
	s_add_i32 s97, s91, 0x9800
	s_add_i32 s98, s91, 0xa800
	s_add_i32 s99, s91, 0xb800
	v_add_u32_e32 v227, s96, v236
	ds_read2_b64 v[248:251], v227 offset0:0 offset1:2
	v_add_u32_e32 v227, s97, v236
	ds_read2_b64 v[252:255], v227 offset0:32 offset1:34
	v_exp_f32_e32 v144, v144
	v_exp_f32_e32 v145, v145
	v_exp_f32_e32 v146, v146
	v_exp_f32_e32 v147, v147
	v_exp_f32_e32 v128, v128
	v_exp_f32_e32 v148, v148
	v_add_f32_e32 v224, v224, v144
	v_exp_f32_e32 v129, v129
	v_exp_f32_e32 v149, v149
	v_add_f32_e32 v224, v224, v145
	v_add_f32_e32 v225, v225, v128
	v_exp_f32_e32 v130, v130
	v_exp_f32_e32 v150, v150
	v_add_f32_e32 v224, v224, v146
	v_add_f32_e32 v225, v225, v129
	v_exp_f32_e32 v131, v131
	v_exp_f32_e32 v151, v151
	v_add_f32_e32 v224, v224, v147
	v_add_f32_e32 v225, v225, v130
	v_exp_f32_e32 v132, v132
	v_add_f32_e32 v224, v224, v148
	v_add_f32_e32 v225, v225, v131
	v_exp_f32_e32 v133, v133
	v_add_f32_e32 v224, v224, v149
	v_add_f32_e32 v225, v225, v132
	v_exp_f32_e32 v134, v134
	v_add_f32_e32 v224, v224, v150
	v_add_f32_e32 v225, v225, v133
	v_exp_f32_e32 v135, v135
	v_add_f32_e32 v224, v224, v151
	v_add_f32_e32 v225, v225, v134
	v_add_f32_e32 v225, v225, v135
	v_cvt_pk_bf16_f32 v144, v144, v145
	v_cvt_pk_bf16_f32 v145, v146, v147
	v_cvt_pk_bf16_f32 v146, v148, v149
	v_cvt_pk_bf16_f32 v147, v150, v151
	v_cvt_pk_bf16_f32 v128, v128, v129
	v_cvt_pk_bf16_f32 v129, v130, v131
	v_cvt_pk_bf16_f32 v130, v132, v133
	v_cvt_pk_bf16_f32 v131, v134, v135
	v_add_u32_e32 v227, s98, v236
	ds_read2_b64 v[148:151], v227 offset0:64 offset1:66
	v_add_u32_e32 v227, s99, v236
	ds_read2_b64 v[132:135], v227 offset0:96 offset1:98
	s_setprio 1
	s_waitcnt lgkmcnt(3)
	v_mfma_f32_32x32x16_bf16 v[64:79], v[248:251], v[144:147], v[64:79]
	v_exp_f32_e32 v152, v152
	v_exp_f32_e32 v153, v153
	v_exp_f32_e32 v154, v154
	v_exp_f32_e32 v155, v155
	v_exp_f32_e32 v136, v136
	v_mfma_f32_32x32x16_bf16 v[112:127], v[248:251], v[128:131], v[112:127]
	v_exp_f32_e32 v156, v156
	v_add_f32_e32 v224, v224, v152
	v_exp_f32_e32 v137, v137
	v_exp_f32_e32 v157, v157
	v_add_f32_e32 v224, v224, v153
	s_waitcnt lgkmcnt(2)
	v_mfma_f32_32x32x16_bf16 v[48:63], v[252:255], v[144:147], v[48:63]
	v_add_u32_e32 v227, s96, v236
	ds_read2_b64 v[248:251], v227 offset0:4 offset1:6
	v_add_f32_e32 v225, v225, v136
	v_exp_f32_e32 v138, v138
	v_exp_f32_e32 v158, v158
	v_add_f32_e32 v224, v224, v154
	v_add_f32_e32 v225, v225, v137
	v_mfma_f32_32x32x16_bf16 v[96:111], v[252:255], v[128:131], v[96:111]
	v_exp_f32_e32 v139, v139
	v_exp_f32_e32 v159, v159
	v_add_f32_e32 v224, v224, v155
	v_add_f32_e32 v225, v225, v138
	v_exp_f32_e32 v140, v140
	s_waitcnt lgkmcnt(2)
	v_mfma_f32_32x32x16_bf16 v[16:31], v[148:151], v[144:147], v[16:31]
	v_add_u32_e32 v227, s97, v236
	ds_read2_b64 v[252:255], v227 offset0:36 offset1:38
	v_add_f32_e32 v224, v224, v156
	v_add_f32_e32 v225, v225, v139
	v_exp_f32_e32 v141, v141
	v_add_f32_e32 v224, v224, v157
	v_add_f32_e32 v225, v225, v140
	v_mfma_f32_32x32x16_bf16 v[80:95], v[148:151], v[128:131], v[80:95]
	v_exp_f32_e32 v142, v142
	v_add_f32_e32 v224, v224, v158
	v_add_f32_e32 v225, v225, v141
	v_exp_f32_e32 v143, v143
	v_add_f32_e32 v224, v224, v159
	s_waitcnt lgkmcnt(2)
	v_mfma_f32_32x32x16_bf16 v[0:15], v[132:135], v[144:147], v[0:15]
	v_add_u32_e32 v227, s98, v236
	ds_read2_b64 v[148:151], v227 offset0:68 offset1:70
	v_add_f32_e32 v225, v225, v142
	v_add_f32_e32 v225, v225, v143
	v_cvt_pk_bf16_f32 v152, v152, v153
	v_cvt_pk_bf16_f32 v153, v154, v155
	v_cvt_pk_bf16_f32 v154, v156, v157
	v_mfma_f32_32x32x16_bf16 v[32:47], v[132:135], v[128:131], v[32:47]
	v_cvt_pk_bf16_f32 v155, v158, v159
	v_cvt_pk_bf16_f32 v136, v136, v137
	v_cvt_pk_bf16_f32 v137, v138, v139
	v_cvt_pk_bf16_f32 v138, v140, v141
	v_cvt_pk_bf16_f32 v139, v142, v143
	s_nop 0
	s_waitcnt lgkmcnt(2)
	v_mfma_f32_32x32x16_bf16 v[64:79], v[248:251], v[152:155], v[64:79]
	v_add_u32_e32 v227, s99, v236
	ds_read2_b64 v[132:135], v227 offset0:100 offset1:102
	v_mfma_f32_32x32x16_bf16 v[112:127], v[248:251], v[136:139], v[112:127]
	s_waitcnt lgkmcnt(2)
	v_mfma_f32_32x32x16_bf16 v[48:63], v[252:255], v[152:155], v[48:63]
	v_mfma_f32_32x32x16_bf16 v[96:111], v[252:255], v[136:139], v[96:111]
	s_waitcnt lgkmcnt(1)
	v_mfma_f32_32x32x16_bf16 v[16:31], v[148:151], v[152:155], v[16:31]
	v_mfma_f32_32x32x16_bf16 v[80:95], v[148:151], v[136:139], v[80:95]
	s_waitcnt lgkmcnt(0)
	v_mfma_f32_32x32x16_bf16 v[0:15], v[132:135], v[152:155], v[0:15]
	v_mfma_f32_32x32x16_bf16 v[32:47], v[132:135], v[136:139], v[32:47]
	s_setprio 0

; #define LAS __attribute__((address_space(3)))
; __device__ __forceinline__ unsigned cvtpk_s(float lo, float hi) { f32x2_t v = {lo, hi}; bf16x2_t b = __builtin_convertvector(v, bf16x2_t); return __builtin_bit_cast(unsigned, b); }
; template <int HF> ...
;     ...
;         float ls = 0.f;
; #pragma unroll
;         for (int r = 0; r < 16; ++r) { p[r] = __builtin_amdgcn_exp2f(p[r]); ls += p[r]; }
;         lsum[sub] += ls;
;         pw[sub][0] = (u32x4){cvtpk_s(p[0], p[1]), cvtpk_s(p[2], p[3]), cvtpk_s(p[4], p[5]), cvtpk_s(p[6], p[7])};
;         pw[sub][1] = (u32x4){cvtpk_s(p[8], p[9]), cvtpk_s(p[10], p[11]), cvtpk_s(p[12], p[13]), cvtpk_s(p[14], p[15])};
;         __builtin_amdgcn_sched_barrier(0);
;         if (sub == 0 && stage) {
;             if (HF == 0) { *(LAS u32x4*)sdst = st0; *(LAS u32x4*)(sdst + 32 * KROW) = st1; }
;             else { *(LAS u32x2*)sdst = (u32x2){st0.x, st0.y}; *(LAS u32x2*)(sdst + 8) = (u32x2){st0.z, st0.w}; *(LAS u32x2*)(sdst + 64 * VROW) = (u32x2){st1.x, st1.y}; *(LAS u32x2*)(sdst + 64 * VROW + 8) = (u32x2){st1.z, st1.w}; }
;             __builtin_amdgcn_sched_barrier(0);
;         }
;     }
;     ...
;     bf16x8 vcur = AT_VFRAG(0);
;     __builtin_amdgcn_s_setprio(1);
; #pragma unroll
;     for (int idx = 0; idx < 8; ++idx) {
;         bf16x8 vnext = vcur;
;         if (idx + 1 < 8) vnext = AT_VFRAG(idx + 1);
;         const int kk = idx >> 2, d = idx & 3;
;         o[0][d] = __builtin_amdgcn_mfma_f32_32x32x16_bf16(vcur, __builtin_bit_cast(bf16x8, pw[0][kk]), o[0][d], 0, 0, 0);
;         o[1][d] = __builtin_amdgcn_mfma_f32_32x32x16_bf16(vcur, __builtin_bit_cast(bf16x8, pw[1][kk]), o[1][d], 0, 0, 0);
;         __builtin_amdgcn_sched_barrier(0);
;         vcur = vnext;
;     }
;     __builtin_amdgcn_s_setprio(0);
.LBB0_272:
	s_add_i32 s96, s91, 0x8800
	s_add_i32 s97, s91, 0x9800
	s_add_i32 s98, s91, 0xa800
	s_add_i32 s99, s91, 0xb800
	v_add_u32_e32 v227, s96, v236
	ds_read2_b64 v[248:251], v227 offset0:8 offset1:10
	v_add_u32_e32 v227, s97, v236
	ds_read2_b64 v[252:255], v227 offset0:40 offset1:42
	v_exp_f32_e32 v144, v144
	v_exp_f32_e32 v145, v145
	v_exp_f32_e32 v146, v146
	v_exp_f32_e32 v147, v147
	v_exp_f32_e32 v128, v128
	v_exp_f32_e32 v148, v148
	v_add_f32_e32 v224, v224, v144
	v_exp_f32_e32 v129, v129
	v_exp_f32_e32 v149, v149
	v_add_f32_e32 v224, v224, v145
	v_add_f32_e32 v225, v225, v128
	v_exp_f32_e32 v130, v130
	v_exp_f32_e32 v150, v150
	v_add_f32_e32 v224, v224, v146
	v_add_f32_e32 v225, v225, v129
	v_exp_f32_e32 v131, v131
	v_exp_f32_e32 v151, v151
	v_add_f32_e32 v224, v224, v147
	v_add_f32_e32 v225, v225, v130
	v_exp_f32_e32 v132, v132
	v_add_f32_e32 v224, v224, v148
	v_add_f32_e32 v225, v225, v131
	v_exp_f32_e32 v133, v133
	v_add_f32_e32 v224, v224, v149
	v_add_f32_e32 v225, v225, v132
	v_exp_f32_e32 v134, v134
	v_add_f32_e32 v224, v224, v150
	v_add_f32_e32 v225, v225, v133
	v_exp_f32_e32 v135, v135
	v_add_f32_e32 v224, v224, v151
	v_add_f32_e32 v225, v225, v134
	v_add_f32_e32 v225, v225, v135
	v_cvt_pk_bf16_f32 v144, v144, v145
	v_cvt_pk_bf16_f32 v145, v146, v147
	v_cvt_pk_bf16_f32 v146, v148, v149
	v_cvt_pk_bf16_f32 v147, v150, v151
	v_cvt_pk_bf16_f32 v128, v128, v129
	v_cvt_pk_bf16_f32 v129, v130, v131
	v_cvt_pk_bf16_f32 v130, v132, v133
	v_cvt_pk_bf16_f32 v131, v134, v135
	v_add_u32_e32 v227, s98, v236
	ds_read2_b64 v[148:151], v227 offset0:72 offset1:74
	v_add_u32_e32 v227, s99, v236
	ds_read2_b64 v[132:135], v227 offset0:104 offset1:106
	s_setprio 1
	s_waitcnt lgkmcnt(3)
	v_mfma_f32_32x32x16_bf16 v[64:79], v[248:251], v[144:147], v[64:79]
	v_exp_f32_e32 v152, v152
	v_exp_f32_e32 v153, v153
	v_exp_f32_e32 v154, v154
	v_exp_f32_e32 v155, v155
	v_exp_f32_e32 v136, v136
	v_mfma_f32_32x32x16_bf16 v[112:127], v[248:251], v[128:131], v[112:127]
	v_exp_f32_e32 v156, v156
	v_add_f32_e32 v224, v224, v152
	v_exp_f32_e32 v137, v137
	v_exp_f32_e32 v157, v157
	v_add_f32_e32 v224, v224, v153
	s_waitcnt lgkmcnt(2)
	v_mfma_f32_32x32x16_bf16 v[48:63], v[252:255], v[144:147], v[48:63]
	v_add_u32_e32 v227, s96, v236
	ds_read2_b64 v[248:251], v227 offset0:12 offset1:14
	v_add_f32_e32 v225, v225, v136
	v_exp_f32_e32 v138, v138
	v_exp_f32_e32 v158, v158
	v_add_f32_e32 v224, v224, v154
	v_add_f32_e32 v225, v225, v137
	v_mfma_f32_32x32x16_bf16 v[96:111], v[252:255], v[128:131], v[96:111]
	v_exp_f32_e32 v139, v139
	v_exp_f32_e32 v159, v159
	v_add_f32_e32 v224, v224, v155
	v_add_f32_e32 v225, v225, v138
	v_exp_f32_e32 v140, v140
	s_waitcnt lgkmcnt(2)
	v_mfma_f32_32x32x16_bf16 v[16:31], v[148:151], v[144:147], v[16:31]
	v_add_u32_e32 v227, s97, v236
	ds_read2_b64 v[252:255], v227 offset0:44 offset1:46
	v_add_f32_e32 v224, v224, v156
	v_add_f32_e32 v225, v225, v139
	v_exp_f32_e32 v141, v141
	v_add_f32_e32 v224, v224, v157
	v_add_f32_e32 v225, v225, v140
	v_mfma_f32_32x32x16_bf16 v[80:95], v[148:151], v[128:131], v[80:95]
	v_exp_f32_e32 v142, v142
	v_add_f32_e32 v224, v224, v158
	v_add_f32_e32 v225, v225, v141
	v_exp_f32_e32 v143, v143
	v_add_f32_e32 v224, v224, v159
	s_waitcnt lgkmcnt(2)
	v_mfma_f32_32x32x16_bf16 v[0:15], v[132:135], v[144:147], v[0:15]
	v_add_u32_e32 v227, s98, v236
	ds_read2_b64 v[148:151], v227 offset0:76 offset1:78
	v_add_f32_e32 v225, v225, v142
	v_add_f32_e32 v225, v225, v143
	v_cvt_pk_bf16_f32 v152, v152, v153
	v_cvt_pk_bf16_f32 v153, v154, v155
	v_cvt_pk_bf16_f32 v154, v156, v157
	v_mfma_f32_32x32x16_bf16 v[32:47], v[132:135], v[128:131], v[32:47]
	v_cvt_pk_bf16_f32 v155, v158, v159
	v_cvt_pk_bf16_f32 v136, v136, v137
	v_cvt_pk_bf16_f32 v137, v138, v139
	v_cvt_pk_bf16_f32 v138, v140, v141
	v_cvt_pk_bf16_f32 v139, v142, v143
	s_nop 0
	s_waitcnt lgkmcnt(2)
	v_mfma_f32_32x32x16_bf16 v[64:79], v[248:251], v[152:155], v[64:79]
	v_add_u32_e32 v227, s99, v236
	ds_read2_b64 v[132:135], v227 offset0:108 offset1:110
	v_mfma_f32_32x32x16_bf16 v[112:127], v[248:251], v[136:139], v[112:127]
	s_waitcnt lgkmcnt(2)
	v_mfma_f32_32x32x16_bf16 v[48:63], v[252:255], v[152:155], v[48:63]
	v_mfma_f32_32x32x16_bf16 v[96:111], v[252:255], v[136:139], v[96:111]
	s_waitcnt lgkmcnt(1)
	v_mfma_f32_32x32x16_bf16 v[16:31], v[148:151], v[152:155], v[16:31]
	v_mfma_f32_32x32x16_bf16 v[80:95], v[148:151], v[136:139], v[80:95]
	s_waitcnt lgkmcnt(0)
	v_mfma_f32_32x32x16_bf16 v[0:15], v[132:135], v[152:155], v[0:15]
	v_mfma_f32_32x32x16_bf16 v[32:47], v[132:135], v[136:139], v[32:47]
	s_setprio 0

; #define LAS __attribute__((address_space(3)))
; __global__ void __launch_bounds__(NTHREADS, 2) fwd_mega(Params P) {
;     extern __shared__ __attribute__((aligned(16))) unsigned char lds_raw[];
;     LAS unsigned char* lds = (LAS unsigned char*)lds_raw;
;     const int G = gridDim.x, bx = blockIdx.x, NGW = G * NWAVES;
;     const int wave_s = __builtin_amdgcn_readfirstlane((int)threadIdx.x >> 6);
;     unsigned* gbar_base = (unsigned*)(P.ws + WS_MISC + 160 * 1024); unsigned gbar_k = 0;
;     const unsigned gbar_ng = G < 8 ? (unsigned)G : 8u, gbar_nx = (unsigned)(G - (bx & 7) + 7) >> 3;
	.amdhsa_kernel _Z8fwd_mega6Params
		.amdhsa_group_segment_fixed_size 0
		.amdhsa_private_segment_fixed_size 0
		.amdhsa_kernarg_size 464
		.amdhsa_user_sgpr_count 2
		.amdhsa_user_sgpr_dispatch_ptr 0
		.amdhsa_user_sgpr_queue_ptr 0
		.amdhsa_user_sgpr_kernarg_segment_ptr 1
		.amdhsa_user_sgpr_dispatch_id 0
		.amdhsa_user_sgpr_kernarg_preload_length 0
		.amdhsa_user_sgpr_kernarg_preload_offset 0
		.amdhsa_user_sgpr_private_segment_size 0
		.amdhsa_uses_dynamic_stack 0
		.amdhsa_enable_private_segment 0
		.amdhsa_system_sgpr_workgroup_id_x 1
		.amdhsa_system_sgpr_workgroup_id_y 0
		.amdhsa_system_sgpr_workgroup_id_z 0
		.amdhsa_system_sgpr_workgroup_info 0
		.amdhsa_system_vgpr_workitem_id 2
		.amdhsa_next_free_vgpr 256
		.amdhsa_next_free_sgpr 102
		.amdhsa_accum_offset 256
		.amdhsa_reserve_vcc 1
		.amdhsa_float_round_mode_32 0
		.amdhsa_float_round_mode_16_64 0
		.amdhsa_float_denorm_mode_32 3
		.amdhsa_float_denorm_mode_16_64 3
		.amdhsa_dx10_clamp 1
		.amdhsa_ieee_mode 1
		.amdhsa_fp16_overflow 0
		.amdhsa_tg_split 0
		.amdhsa_exception_fp_ieee_invalid_op 0
		.amdhsa_exception_fp_denorm_src 0
		.amdhsa_exception_fp_ieee_div_zero 0
		.amdhsa_exception_fp_ieee_overflow 0
		.amdhsa_exception_fp_ieee_underflow 0
		.amdhsa_exception_fp_ieee_inexact 0
		.amdhsa_exception_int_div_zero 0
	.end_amdhsa_kernel

; #define LAS __attribute__((address_space(3)))
; __global__ void __launch_bounds__(NTHREADS, 2) fwd_mega(Params P) {
;     extern __shared__ __attribute__((aligned(16))) unsigned char lds_raw[];
;     LAS unsigned char* lds = (LAS unsigned char*)lds_raw;
;     const int G = gridDim.x, bx = blockIdx.x, NGW = G * NWAVES;
;     const int wave_s = __builtin_amdgcn_readfirstlane((int)threadIdx.x >> 6);
;     unsigned* gbar_base = (unsigned*)(P.ws + WS_MISC + 160 * 1024); unsigned gbar_k = 0;
;     const unsigned gbar_ng = G < 8 ? (unsigned)G : 8u, gbar_nx = (unsigned)(G - (bx & 7) + 7) >> 3;
amdhsa.kernels:
  - .agpr_count:     0
    .args:
      - .offset:         0
        .size:           208
        .value_kind:     by_value
      - .offset:         208
        .size:           4
        .value_kind:     hidden_block_count_x
      - .offset:         212
        .size:           4
        .value_kind:     hidden_block_count_y
      - .offset:         216
        .size:           4
        .value_kind:     hidden_block_count_z
      - .offset:         220
        .size:           2
        .value_kind:     hidden_group_size_x
      - .offset:         222
        .size:           2
        .value_kind:     hidden_group_size_y
      - .offset:         224
        .size:           2
        .value_kind:     hidden_group_size_z
      - .offset:         226
        .size:           2
        .value_kind:     hidden_remainder_x
      - .offset:         228
        .size:           2
        .value_kind:     hidden_remainder_y
      - .offset:         230
        .size:           2
        .value_kind:     hidden_remainder_z
      - .offset:         248
        .size:           8
        .value_kind:     hidden_global_offset_x
      - .offset:         256
        .size:           8
        .value_kind:     hidden_global_offset_y
      - .offset:         264
        .size:           8
        .value_kind:     hidden_global_offset_z
      - .offset:         272
        .size:           2
        .value_kind:     hidden_grid_dims
      - .offset:         296
        .size:           8
        .value_kind:     hidden_multigrid_sync_arg
      - .offset:         328
        .size:           4
        .value_kind:     hidden_dynamic_lds_size
    .group_segment_fixed_size: 0
    .kernarg_segment_align: 8
    .kernarg_segment_size: 464
    .language:       OpenCL C
    .language_version:
      - 2
      - 0
    .max_flat_workgroup_size: 512
    .name:           _Z8fwd_mega6Params
    .private_segment_fixed_size: 0
    .sgpr_count:     108
    .sgpr_spill_count: 0
    .symbol:         _Z8fwd_mega6Params.kd
    .uniform_work_group_size: 1
    .uses_dynamic_stack: false
    .vgpr_count:     256
    .vgpr_spill_count: 0
    .wavefront_size: 64
